# GEMM K-loops: LDS-DMA stage instructions in saddr form (SGPR base + 32-bit lane offset), 12-16 of 16 per iteration; 64-bit VGPR address adds dropped
# baseline (speedup 1.0000x reference)
.LBB0_267:
	ds_read_b128 v[128:131], v225
	ds_read_b128 v[132:135], v225 offset:1024
	ds_read_b128 v[136:139], v225 offset:2048
	ds_read_b128 v[140:143], v225 offset:3072
	ds_read_b128 v[144:147], v226
	ds_read_b128 v[148:151], v226 offset:1024
	ds_read_b128 v[152:155], v226 offset:2048
	ds_read_b128 v[156:159], v226 offset:3072
	s_add_u32 s20, s52, 0xfffc0080
	s_addc_u32 s21, s53, -1
	s_cmp_eq_u32 vcc_lo, 12
	s_cselect_b32 s57, s43, s21
	s_cselect_b32 s56, s51, s20
	s_cselect_b32 s55, s41, s97
	s_cselect_b32 s54, s87, s96
	s_add_i32 m0, s49, 0xc000
	ds_read_b128 v[160:163], v227
	ds_read_b128 v[164:167], v227 offset:1024
	ds_read_b128 v[168:171], v227 offset:2048
	ds_read_b128 v[172:175], v227 offset:3072
	ds_read_b128 v[176:179], v227 offset:4096
	ds_read_b128 v[180:183], v227 offset:5120
	ds_read_b128 v[184:187], v227 offset:6144
	ds_read_b128 v[188:191], v227 offset:7168
	global_load_lds_dwordx4 v206, s[52:53]
	s_add_i32 m0, s49, 0xe000
	s_nop 0
	global_load_lds_dwordx4 v210, s[52:53]
	s_waitcnt vmcnt(8)
	s_waitcnt lgkmcnt(0)
	s_barrier
	s_setprio 1
	s_waitcnt lgkmcnt(0)
	v_mfma_f32_16x16x32_bf16 v[76:79], v[128:131], v[160:163], v[76:79]
	v_mfma_f32_16x16x32_bf16 v[68:71], v[136:139], v[160:163], v[68:71]
	v_mfma_f32_16x16x32_bf16 v[60:63], v[128:131], v[168:171], v[60:63]
	v_mfma_f32_16x16x32_bf16 v[56:59], v[136:139], v[168:171], v[56:59]
	v_mfma_f32_16x16x32_bf16 v[52:55], v[128:131], v[176:179], v[52:55]
	v_mfma_f32_16x16x32_bf16 v[48:51], v[136:139], v[176:179], v[48:51]
	v_mfma_f32_16x16x32_bf16 v[44:47], v[128:131], v[184:187], v[44:47]
	v_mfma_f32_16x16x32_bf16 v[40:43], v[136:139], v[184:187], v[40:43]
	v_mfma_f32_16x16x32_bf16 v[76:79], v[132:135], v[164:167], v[76:79]
	v_mfma_f32_16x16x32_bf16 v[68:71], v[140:143], v[164:167], v[68:71]
	v_mfma_f32_16x16x32_bf16 v[60:63], v[132:135], v[172:175], v[60:63]
	v_mfma_f32_16x16x32_bf16 v[56:59], v[140:143], v[172:175], v[56:59]
	v_mfma_f32_16x16x32_bf16 v[52:55], v[132:135], v[180:183], v[52:55]
	v_mfma_f32_16x16x32_bf16 v[48:51], v[140:143], v[180:183], v[48:51]
	v_mfma_f32_16x16x32_bf16 v[44:47], v[132:135], v[188:191], v[44:47]
	v_mfma_f32_16x16x32_bf16 v[40:43], v[140:143], v[188:191], v[40:43]
	s_setprio 0
	s_setprio 1
	v_mfma_f32_16x16x32_bf16 v[124:127], v[144:147], v[160:163], v[124:127]
	v_mfma_f32_16x16x32_bf16 v[120:123], v[152:155], v[160:163], v[120:123]
	v_mfma_f32_16x16x32_bf16 v[116:119], v[144:147], v[168:171], v[116:119]
	v_mfma_f32_16x16x32_bf16 v[112:115], v[152:155], v[168:171], v[112:115]
	v_mfma_f32_16x16x32_bf16 v[108:111], v[144:147], v[176:179], v[108:111]
	v_mfma_f32_16x16x32_bf16 v[104:107], v[152:155], v[176:179], v[104:107]
	v_mfma_f32_16x16x32_bf16 v[100:103], v[144:147], v[184:187], v[100:103]
	v_mfma_f32_16x16x32_bf16 v[96:99], v[152:155], v[184:187], v[96:99]
	v_mfma_f32_16x16x32_bf16 v[124:127], v[148:151], v[164:167], v[124:127]
	v_mfma_f32_16x16x32_bf16 v[120:123], v[156:159], v[164:167], v[120:123]
	v_mfma_f32_16x16x32_bf16 v[116:119], v[148:151], v[172:175], v[116:119]
	v_mfma_f32_16x16x32_bf16 v[112:115], v[156:159], v[172:175], v[112:115]
	v_mfma_f32_16x16x32_bf16 v[108:111], v[148:151], v[180:183], v[108:111]
	v_mfma_f32_16x16x32_bf16 v[104:107], v[156:159], v[180:183], v[104:107]
	v_mfma_f32_16x16x32_bf16 v[100:103], v[148:151], v[188:191], v[100:103]
	v_mfma_f32_16x16x32_bf16 v[96:99], v[156:159], v[188:191], v[96:99]
	s_setprio 0
	s_barrier
	s_add_i32 s20, s84, s3
	s_mov_b32 m0, s20
	ds_read_b128 v[160:163], v227 offset:16384
	ds_read_b128 v[164:167], v227 offset:17408
	ds_read_b128 v[168:171], v227 offset:18432
	ds_read_b128 v[172:175], v227 offset:19456
	ds_read_b128 v[176:179], v227 offset:20480
	ds_read_b128 v[180:183], v227 offset:21504
	ds_read_b128 v[184:187], v227 offset:22528
	ds_read_b128 v[188:191], v227 offset:23552
	global_load_lds_dwordx4 v194, s[54:55]
	s_add_i32 m0, s20, 0x2000
	s_add_u32 s20, s54, 0x40000
	s_addc_u32 s21, s55, 0
	s_add_i32 vcc_hi, s85, s3
	global_load_lds_dwordx4 v198, s[54:55]
	s_mov_b32 m0, vcc_hi
	global_load_lds_dwordx4 v194, s[20:21]
	s_add_i32 m0, vcc_hi, 0x2000
	s_nop 0
	global_load_lds_dwordx4 v198, s[20:21]
	s_mov_b32 m0, s49
	s_nop 0
	global_load_lds_dwordx4 v192, s[56:57]
	s_mov_b32 m0, s59
	s_nop 0
	global_load_lds_dwordx4 v196, s[56:57]
	s_waitcnt vmcnt(8)
	s_waitcnt lgkmcnt(0)
	s_barrier
	s_setprio 1
	s_waitcnt lgkmcnt(0)
	v_mfma_f32_16x16x32_bf16 v[28:31], v[128:131], v[160:163], v[28:31]
	v_mfma_f32_16x16x32_bf16 v[24:27], v[136:139], v[160:163], v[24:27]
	v_mfma_f32_16x16x32_bf16 v[20:23], v[128:131], v[168:171], v[20:23]
	v_mfma_f32_16x16x32_bf16 v[16:19], v[136:139], v[168:171], v[16:19]
	v_mfma_f32_16x16x32_bf16 v[12:15], v[128:131], v[176:179], v[12:15]
	v_mfma_f32_16x16x32_bf16 v[8:11], v[136:139], v[176:179], v[8:11]
	v_mfma_f32_16x16x32_bf16 v[4:7], v[128:131], v[184:187], v[4:7]
	v_mfma_f32_16x16x32_bf16 v[0:3], v[136:139], v[184:187], v[0:3]
	v_mfma_f32_16x16x32_bf16 v[28:31], v[132:135], v[164:167], v[28:31]
	v_mfma_f32_16x16x32_bf16 v[24:27], v[140:143], v[164:167], v[24:27]
	v_mfma_f32_16x16x32_bf16 v[20:23], v[132:135], v[172:175], v[20:23]
	v_mfma_f32_16x16x32_bf16 v[16:19], v[140:143], v[172:175], v[16:19]
	v_mfma_f32_16x16x32_bf16 v[12:15], v[132:135], v[180:183], v[12:15]
	v_mfma_f32_16x16x32_bf16 v[8:11], v[140:143], v[180:183], v[8:11]
	v_mfma_f32_16x16x32_bf16 v[4:7], v[132:135], v[188:191], v[4:7]
	v_mfma_f32_16x16x32_bf16 v[0:3], v[140:143], v[188:191], v[0:3]
	s_setprio 0
	s_setprio 1
	v_mfma_f32_16x16x32_bf16 v[92:95], v[144:147], v[160:163], v[92:95]
	v_mfma_f32_16x16x32_bf16 v[88:91], v[152:155], v[160:163], v[88:91]
	v_mfma_f32_16x16x32_bf16 v[84:87], v[144:147], v[168:171], v[84:87]
	v_mfma_f32_16x16x32_bf16 v[80:83], v[152:155], v[168:171], v[80:83]
	v_mfma_f32_16x16x32_bf16 v[72:75], v[144:147], v[176:179], v[72:75]
	v_mfma_f32_16x16x32_bf16 v[64:67], v[152:155], v[176:179], v[64:67]
	v_mfma_f32_16x16x32_bf16 v[36:39], v[144:147], v[184:187], v[36:39]
	v_mfma_f32_16x16x32_bf16 v[32:35], v[152:155], v[184:187], v[32:35]
	v_mfma_f32_16x16x32_bf16 v[92:95], v[148:151], v[164:167], v[92:95]
	v_mfma_f32_16x16x32_bf16 v[88:91], v[156:159], v[164:167], v[88:91]
	v_mfma_f32_16x16x32_bf16 v[84:87], v[148:151], v[172:175], v[84:87]
	v_mfma_f32_16x16x32_bf16 v[80:83], v[156:159], v[172:175], v[80:83]
	v_mfma_f32_16x16x32_bf16 v[72:75], v[148:151], v[180:183], v[72:75]
	v_mfma_f32_16x16x32_bf16 v[64:67], v[156:159], v[180:183], v[64:67]
	v_mfma_f32_16x16x32_bf16 v[36:39], v[148:151], v[188:191], v[36:39]
	v_mfma_f32_16x16x32_bf16 v[32:35], v[156:159], v[188:191], v[32:35]
	s_setprio 0
	s_barrier
	s_add_i32 vcc_hi, 0, 0x18000
	s_add_i32 s18, 0, 0x1c000
	v_add_u32_e32 v140, vcc_hi, v209
	v_add_u32_e32 v156, s18, v209
	ds_read_b128 v[128:131], v140
	ds_read_b128 v[132:135], v140 offset:1024
	ds_read_b128 v[136:139], v140 offset:2048
	ds_read_b128 v[140:143], v140 offset:3072
	ds_read_b128 v[144:147], v156
	ds_read_b128 v[148:151], v156 offset:1024
	ds_read_b128 v[152:155], v156 offset:2048
	ds_read_b128 v[156:159], v156 offset:3072
	s_add_u32 s20, s56, 0x40000
	s_addc_u32 s21, s57, 0
	s_mov_b32 m0, s62
	ds_read_b128 v[160:163], v227 offset:32768
	ds_read_b128 v[164:167], v227 offset:33792
	ds_read_b128 v[168:171], v227 offset:34816
	ds_read_b128 v[172:175], v227 offset:35840
	ds_read_b128 v[176:179], v227 offset:36864
	ds_read_b128 v[180:183], v227 offset:37888
	ds_read_b128 v[184:187], v227 offset:38912
	ds_read_b128 v[188:191], v227 offset:39936
	global_load_lds_dwordx4 v192, s[20:21]
	s_mov_b32 m0, s63
	s_nop 0
	global_load_lds_dwordx4 v196, s[20:21]
	s_waitcnt vmcnt(8)
	s_waitcnt lgkmcnt(0)
	s_barrier
	s_setprio 1
	s_waitcnt lgkmcnt(0)
	v_mfma_f32_16x16x32_bf16 v[76:79], v[128:131], v[160:163], v[76:79]
	v_mfma_f32_16x16x32_bf16 v[68:71], v[136:139], v[160:163], v[68:71]
	v_mfma_f32_16x16x32_bf16 v[60:63], v[128:131], v[168:171], v[60:63]
	v_mfma_f32_16x16x32_bf16 v[56:59], v[136:139], v[168:171], v[56:59]
	v_mfma_f32_16x16x32_bf16 v[52:55], v[128:131], v[176:179], v[52:55]
	v_mfma_f32_16x16x32_bf16 v[48:51], v[136:139], v[176:179], v[48:51]
	v_mfma_f32_16x16x32_bf16 v[44:47], v[128:131], v[184:187], v[44:47]
	v_mfma_f32_16x16x32_bf16 v[40:43], v[136:139], v[184:187], v[40:43]
	v_mfma_f32_16x16x32_bf16 v[76:79], v[132:135], v[164:167], v[76:79]
	v_mfma_f32_16x16x32_bf16 v[68:71], v[140:143], v[164:167], v[68:71]
	v_mfma_f32_16x16x32_bf16 v[60:63], v[132:135], v[172:175], v[60:63]
	v_mfma_f32_16x16x32_bf16 v[56:59], v[140:143], v[172:175], v[56:59]
	v_mfma_f32_16x16x32_bf16 v[52:55], v[132:135], v[180:183], v[52:55]
	v_mfma_f32_16x16x32_bf16 v[48:51], v[140:143], v[180:183], v[48:51]
	v_mfma_f32_16x16x32_bf16 v[44:47], v[132:135], v[188:191], v[44:47]
	v_mfma_f32_16x16x32_bf16 v[40:43], v[140:143], v[188:191], v[40:43]
	s_setprio 0
	s_setprio 1
	v_mfma_f32_16x16x32_bf16 v[124:127], v[144:147], v[160:163], v[124:127]
	v_mfma_f32_16x16x32_bf16 v[120:123], v[152:155], v[160:163], v[120:123]
	v_mfma_f32_16x16x32_bf16 v[116:119], v[144:147], v[168:171], v[116:119]
	v_mfma_f32_16x16x32_bf16 v[112:115], v[152:155], v[168:171], v[112:115]
	v_mfma_f32_16x16x32_bf16 v[108:111], v[144:147], v[176:179], v[108:111]
	v_mfma_f32_16x16x32_bf16 v[104:107], v[152:155], v[176:179], v[104:107]
	v_mfma_f32_16x16x32_bf16 v[100:103], v[144:147], v[184:187], v[100:103]
	v_mfma_f32_16x16x32_bf16 v[96:99], v[152:155], v[184:187], v[96:99]
	v_mfma_f32_16x16x32_bf16 v[124:127], v[148:151], v[164:167], v[124:127]
	v_mfma_f32_16x16x32_bf16 v[120:123], v[156:159], v[164:167], v[120:123]
	v_mfma_f32_16x16x32_bf16 v[116:119], v[148:151], v[172:175], v[116:119]
	v_mfma_f32_16x16x32_bf16 v[112:115], v[156:159], v[172:175], v[112:115]
	v_mfma_f32_16x16x32_bf16 v[108:111], v[148:151], v[180:183], v[108:111]
	v_mfma_f32_16x16x32_bf16 v[104:107], v[156:159], v[180:183], v[104:107]
	v_mfma_f32_16x16x32_bf16 v[100:103], v[148:151], v[188:191], v[100:103]
	v_mfma_f32_16x16x32_bf16 v[96:99], v[156:159], v[188:191], v[96:99]
	s_setprio 0
	s_barrier
	s_add_i32 s19, vcc_hi, s3
	s_mov_b32 m0, s19
	ds_read_b128 v[160:163], v227 offset:49152
	ds_read_b128 v[164:167], v227 offset:50176
	ds_read_b128 v[168:171], v227 offset:51200
	ds_read_b128 v[172:175], v227 offset:52224
	ds_read_b128 v[176:179], v227 offset:53248
	ds_read_b128 v[180:183], v227 offset:54272
	ds_read_b128 v[184:187], v227 offset:55296
	ds_read_b128 v[188:191], v227 offset:56320
	s_add_u32 s98, s54, s26
	s_addc_u32 s99, s55, s27
	global_load_lds_dwordx4 v194, s[98:99]
	s_add_i32 m0, s19, 0x2000
	s_add_u32 s20, s54, 0x40080
	s_addc_u32 s21, s55, 0
	s_add_i32 s18, s18, s3
	s_add_u32 s100, s54, s26
	s_addc_u32 s101, s55, s27
	global_load_lds_dwordx4 v198, s[100:101]
	s_mov_b32 m0, s18
	s_nop 0
	global_load_lds_dwordx4 v194, s[20:21]
	s_add_i32 m0, s18, 0x2000
	s_nop 0
	global_load_lds_dwordx4 v198, s[20:21]
	s_mov_b32 m0, s68
	s_nop 0
	s_add_u32 s98, s56, s26
	s_addc_u32 s99, s57, s27
	global_load_lds_dwordx4 v192, s[98:99]
	s_mov_b32 m0, s69
	s_nop 0
	s_add_u32 s100, s56, s26
	s_addc_u32 s101, s57, s27
	global_load_lds_dwordx4 v196, s[100:101]
	s_waitcnt vmcnt(8)
	s_waitcnt lgkmcnt(0)
	s_barrier
	s_setprio 1
	s_waitcnt lgkmcnt(0)
	v_mfma_f32_16x16x32_bf16 v[28:31], v[128:131], v[160:163], v[28:31]
	v_mfma_f32_16x16x32_bf16 v[24:27], v[136:139], v[160:163], v[24:27]
	v_mfma_f32_16x16x32_bf16 v[20:23], v[128:131], v[168:171], v[20:23]
	v_mfma_f32_16x16x32_bf16 v[16:19], v[136:139], v[168:171], v[16:19]
	v_mfma_f32_16x16x32_bf16 v[12:15], v[128:131], v[176:179], v[12:15]
	v_mfma_f32_16x16x32_bf16 v[8:11], v[136:139], v[176:179], v[8:11]
	v_mfma_f32_16x16x32_bf16 v[4:7], v[128:131], v[184:187], v[4:7]
	v_mfma_f32_16x16x32_bf16 v[0:3], v[136:139], v[184:187], v[0:3]
	v_mfma_f32_16x16x32_bf16 v[28:31], v[132:135], v[164:167], v[28:31]
	v_mfma_f32_16x16x32_bf16 v[24:27], v[140:143], v[164:167], v[24:27]
	v_mfma_f32_16x16x32_bf16 v[20:23], v[132:135], v[172:175], v[20:23]
	v_mfma_f32_16x16x32_bf16 v[16:19], v[140:143], v[172:175], v[16:19]
	v_mfma_f32_16x16x32_bf16 v[12:15], v[132:135], v[180:183], v[12:15]
	v_mfma_f32_16x16x32_bf16 v[8:11], v[140:143], v[180:183], v[8:11]
	v_mfma_f32_16x16x32_bf16 v[4:7], v[132:135], v[188:191], v[4:7]
	v_mfma_f32_16x16x32_bf16 v[0:3], v[140:143], v[188:191], v[0:3]
	s_setprio 0
	s_setprio 1
	v_mfma_f32_16x16x32_bf16 v[92:95], v[144:147], v[160:163], v[92:95]
	v_mfma_f32_16x16x32_bf16 v[88:91], v[152:155], v[160:163], v[88:91]
	v_mfma_f32_16x16x32_bf16 v[84:87], v[144:147], v[168:171], v[84:87]
	v_mfma_f32_16x16x32_bf16 v[80:83], v[152:155], v[168:171], v[80:83]
	v_mfma_f32_16x16x32_bf16 v[72:75], v[144:147], v[176:179], v[72:75]
	v_mfma_f32_16x16x32_bf16 v[64:67], v[152:155], v[176:179], v[64:67]
	v_mfma_f32_16x16x32_bf16 v[36:39], v[144:147], v[184:187], v[36:39]
	v_mfma_f32_16x16x32_bf16 v[32:35], v[152:155], v[184:187], v[32:35]
	v_mfma_f32_16x16x32_bf16 v[92:95], v[148:151], v[164:167], v[92:95]
	v_mfma_f32_16x16x32_bf16 v[88:91], v[156:159], v[164:167], v[88:91]
	v_mfma_f32_16x16x32_bf16 v[84:87], v[148:151], v[172:175], v[84:87]
	v_mfma_f32_16x16x32_bf16 v[80:83], v[156:159], v[172:175], v[80:83]
	v_mfma_f32_16x16x32_bf16 v[72:75], v[148:151], v[180:183], v[72:75]
	v_mfma_f32_16x16x32_bf16 v[64:67], v[156:159], v[180:183], v[64:67]
	v_mfma_f32_16x16x32_bf16 v[36:39], v[148:151], v[188:191], v[36:39]
	v_mfma_f32_16x16x32_bf16 v[32:35], v[156:159], v[188:191], v[32:35]
	s_setprio 0
	s_barrier
	s_add_i32 vcc_lo, vcc_lo, 2
	s_add_u32 s52, s52, 0x100
	s_addc_u32 s53, s53, 0
	s_add_u32 s96, s96, 0x100
	s_addc_u32 s97, s97, 0
	s_cmp_gt_u32 vcc_lo, 13
	s_cbranch_scc0 .LBB0_267
	s_and_b64 vcc, exec, s[28:29]
	s_cbranch_vccnz .LBB0_271
	v_lshl_add_u32 v216, s50, 8, v203
	s_cmp_lg_u32 s48, 32
	s_mov_b64 s[50:51], -1
	s_cbranch_scc1 .LBB0_272

.LBB0_1046:
	ds_read_b128 v[128:131], v207
	ds_read_b128 v[132:135], v207 offset:1024
	ds_read_b128 v[136:139], v207 offset:2048
	ds_read_b128 v[140:143], v207 offset:3072
	ds_read_b128 v[144:147], v209
	ds_read_b128 v[148:151], v209 offset:1024
	ds_read_b128 v[152:155], v209 offset:2048
	ds_read_b128 v[156:159], v209 offset:3072
	s_add_u32 s34, s30, 0xfffc0080
	s_addc_u32 s35, s31, -1
	s_cmp_eq_u32 s55, 12
	s_cselect_b32 s37, s21, s35
	s_cselect_b32 s36, s27, s34
	s_cselect_b32 s35, s19, s54
	s_cselect_b32 s34, s52, s53
	s_add_i32 m0, s29, 0xc000
	ds_read_b128 v[160:163], v210
	ds_read_b128 v[164:167], v210 offset:1024
	ds_read_b128 v[168:171], v210 offset:2048
	ds_read_b128 v[172:175], v210 offset:3072
	ds_read_b128 v[192:195], v210 offset:4096
	ds_read_b128 v[196:199], v210 offset:5120
	ds_read_b128 v[200:203], v210 offset:6144
	ds_read_b128 v[212:215], v210 offset:7168
	global_load_lds_dwordx4 v184, s[30:31]
	s_add_i32 m0, s29, 0xe000
	s_nop 0
	global_load_lds_dwordx4 v186, s[30:31]
	s_waitcnt vmcnt(8)
	s_waitcnt lgkmcnt(0)
	s_barrier
	s_setprio 1
	s_waitcnt lgkmcnt(0)
	v_mfma_f32_16x16x32_bf16 v[124:127], v[128:131], v[160:163], v[124:127]
	v_mfma_f32_16x16x32_bf16 v[120:123], v[136:139], v[160:163], v[120:123]
	v_mfma_f32_16x16x32_bf16 v[108:111], v[128:131], v[168:171], v[108:111]
	v_mfma_f32_16x16x32_bf16 v[104:107], v[136:139], v[168:171], v[104:107]
	v_mfma_f32_16x16x32_bf16 v[92:95], v[128:131], v[192:195], v[92:95]
	v_mfma_f32_16x16x32_bf16 v[88:91], v[136:139], v[192:195], v[88:91]
	v_mfma_f32_16x16x32_bf16 v[76:79], v[128:131], v[200:203], v[76:79]
	v_mfma_f32_16x16x32_bf16 v[72:75], v[136:139], v[200:203], v[72:75]
	v_mfma_f32_16x16x32_bf16 v[124:127], v[132:135], v[164:167], v[124:127]
	v_mfma_f32_16x16x32_bf16 v[120:123], v[140:143], v[164:167], v[120:123]
	v_mfma_f32_16x16x32_bf16 v[108:111], v[132:135], v[172:175], v[108:111]
	v_mfma_f32_16x16x32_bf16 v[104:107], v[140:143], v[172:175], v[104:107]
	v_mfma_f32_16x16x32_bf16 v[92:95], v[132:135], v[196:199], v[92:95]
	v_mfma_f32_16x16x32_bf16 v[88:91], v[140:143], v[196:199], v[88:91]
	v_mfma_f32_16x16x32_bf16 v[76:79], v[132:135], v[212:215], v[76:79]
	v_mfma_f32_16x16x32_bf16 v[72:75], v[140:143], v[212:215], v[72:75]
	s_setprio 0
	s_setprio 1
	v_mfma_f32_16x16x32_bf16 v[116:119], v[144:147], v[160:163], v[116:119]
	v_mfma_f32_16x16x32_bf16 v[112:115], v[152:155], v[160:163], v[112:115]
	v_mfma_f32_16x16x32_bf16 v[100:103], v[144:147], v[168:171], v[100:103]
	v_mfma_f32_16x16x32_bf16 v[96:99], v[152:155], v[168:171], v[96:99]
	v_mfma_f32_16x16x32_bf16 v[84:87], v[144:147], v[192:195], v[84:87]
	v_mfma_f32_16x16x32_bf16 v[80:83], v[152:155], v[192:195], v[80:83]
	v_mfma_f32_16x16x32_bf16 v[68:71], v[144:147], v[200:203], v[68:71]
	v_mfma_f32_16x16x32_bf16 v[64:67], v[152:155], v[200:203], v[64:67]
	v_mfma_f32_16x16x32_bf16 v[116:119], v[148:151], v[164:167], v[116:119]
	v_mfma_f32_16x16x32_bf16 v[112:115], v[156:159], v[164:167], v[112:115]
	v_mfma_f32_16x16x32_bf16 v[100:103], v[148:151], v[172:175], v[100:103]
	v_mfma_f32_16x16x32_bf16 v[96:99], v[156:159], v[172:175], v[96:99]
	v_mfma_f32_16x16x32_bf16 v[84:87], v[148:151], v[196:199], v[84:87]
	v_mfma_f32_16x16x32_bf16 v[80:83], v[156:159], v[196:199], v[80:83]
	v_mfma_f32_16x16x32_bf16 v[68:71], v[148:151], v[212:215], v[68:71]
	v_mfma_f32_16x16x32_bf16 v[64:67], v[156:159], v[212:215], v[64:67]
	s_setprio 0
	s_barrier
	s_add_i32 s56, s50, s40
	s_mov_b32 m0, s56
	ds_read_b128 v[160:163], v210 offset:16384
	ds_read_b128 v[164:167], v210 offset:17408
	ds_read_b128 v[168:171], v210 offset:18432
	ds_read_b128 v[172:175], v210 offset:19456
	ds_read_b128 v[192:195], v210 offset:20480
	ds_read_b128 v[196:199], v210 offset:21504
	ds_read_b128 v[200:203], v210 offset:22528
	ds_read_b128 v[212:215], v210 offset:23552
	global_load_lds_dwordx4 v178, s[34:35]
	s_add_i32 m0, s56, 0x2000
	s_add_u32 s56, s34, 0x40000
	v_lshl_add_u64 v[218:219], s[34:35], 0, v[182:183]
	s_addc_u32 s57, s35, 0
	s_add_i32 s58, s51, s40
	global_load_lds_dwordx4 v182, s[34:35]
	s_mov_b32 m0, s58
	v_lshl_add_u64 v[222:223], s[36:37], 0, v[180:181]
	global_load_lds_dwordx4 v178, s[56:57]
	s_add_i32 m0, s58, 0x2000
	s_nop 0
	global_load_lds_dwordx4 v182, s[56:57]
	v_lshl_add_u64 v[220:221], s[36:37], 0, v[176:177]
	s_mov_b32 m0, s29
	s_nop 0
	global_load_lds_dwordx4 v176, s[36:37]
	s_mov_b32 m0, s41
	s_nop 0
	global_load_lds_dwordx4 v180, s[36:37]
	s_waitcnt vmcnt(8)
	s_waitcnt lgkmcnt(0)
	s_barrier
	s_setprio 1
	s_waitcnt lgkmcnt(0)
	v_mfma_f32_16x16x32_bf16 v[60:63], v[128:131], v[160:163], v[60:63]
	v_mfma_f32_16x16x32_bf16 v[56:59], v[136:139], v[160:163], v[56:59]
	v_mfma_f32_16x16x32_bf16 v[44:47], v[128:131], v[168:171], v[44:47]
	v_mfma_f32_16x16x32_bf16 v[40:43], v[136:139], v[168:171], v[40:43]
	v_mfma_f32_16x16x32_bf16 v[28:31], v[128:131], v[192:195], v[28:31]
	v_mfma_f32_16x16x32_bf16 v[24:27], v[136:139], v[192:195], v[24:27]
	v_mfma_f32_16x16x32_bf16 v[12:15], v[128:131], v[200:203], v[12:15]
	v_mfma_f32_16x16x32_bf16 v[8:11], v[136:139], v[200:203], v[8:11]
	v_mfma_f32_16x16x32_bf16 v[60:63], v[132:135], v[164:167], v[60:63]
	v_mfma_f32_16x16x32_bf16 v[56:59], v[140:143], v[164:167], v[56:59]
	v_mfma_f32_16x16x32_bf16 v[44:47], v[132:135], v[172:175], v[44:47]
	v_mfma_f32_16x16x32_bf16 v[40:43], v[140:143], v[172:175], v[40:43]
	v_mfma_f32_16x16x32_bf16 v[28:31], v[132:135], v[196:199], v[28:31]
	v_mfma_f32_16x16x32_bf16 v[24:27], v[140:143], v[196:199], v[24:27]
	v_mfma_f32_16x16x32_bf16 v[12:15], v[132:135], v[212:215], v[12:15]
	v_mfma_f32_16x16x32_bf16 v[8:11], v[140:143], v[212:215], v[8:11]
	s_setprio 0
	s_setprio 1
	v_mfma_f32_16x16x32_bf16 v[52:55], v[144:147], v[160:163], v[52:55]
	v_mfma_f32_16x16x32_bf16 v[48:51], v[152:155], v[160:163], v[48:51]
	v_mfma_f32_16x16x32_bf16 v[36:39], v[144:147], v[168:171], v[36:39]
	v_mfma_f32_16x16x32_bf16 v[32:35], v[152:155], v[168:171], v[32:35]
	v_mfma_f32_16x16x32_bf16 v[20:23], v[144:147], v[192:195], v[20:23]
	v_mfma_f32_16x16x32_bf16 v[16:19], v[152:155], v[192:195], v[16:19]
	v_mfma_f32_16x16x32_bf16 v[4:7], v[144:147], v[200:203], v[4:7]
	v_mfma_f32_16x16x32_bf16 v[0:3], v[152:155], v[200:203], v[0:3]
	v_mfma_f32_16x16x32_bf16 v[52:55], v[148:151], v[164:167], v[52:55]
	v_mfma_f32_16x16x32_bf16 v[48:51], v[156:159], v[164:167], v[48:51]
	v_mfma_f32_16x16x32_bf16 v[36:39], v[148:151], v[172:175], v[36:39]
	v_mfma_f32_16x16x32_bf16 v[32:35], v[156:159], v[172:175], v[32:35]
	v_mfma_f32_16x16x32_bf16 v[20:23], v[148:151], v[196:199], v[20:23]
	v_mfma_f32_16x16x32_bf16 v[16:19], v[156:159], v[196:199], v[16:19]
	v_mfma_f32_16x16x32_bf16 v[4:7], v[148:151], v[212:215], v[4:7]
	v_mfma_f32_16x16x32_bf16 v[0:3], v[156:159], v[212:215], v[0:3]
	s_setprio 0
	s_barrier
	s_add_i32 s56, 0, 0x18000
	s_add_i32 s57, 0, 0x1c000
	v_add_u32_e32 v140, s56, v205
	v_add_u32_e32 v156, s57, v205
	ds_read_b128 v[128:131], v140
	ds_read_b128 v[132:135], v140 offset:1024
	ds_read_b128 v[136:139], v140 offset:2048
	ds_read_b128 v[140:143], v140 offset:3072
	ds_read_b128 v[144:147], v156
	ds_read_b128 v[148:151], v156 offset:1024
	ds_read_b128 v[152:155], v156 offset:2048
	ds_read_b128 v[156:159], v156 offset:3072
	s_add_u32 s36, s36, 0x40000
	s_addc_u32 s37, s37, 0
	s_mov_b32 m0, s42
	ds_read_b128 v[160:163], v210 offset:32768
	ds_read_b128 v[164:167], v210 offset:33792
	ds_read_b128 v[168:171], v210 offset:34816
	ds_read_b128 v[172:175], v210 offset:35840
	ds_read_b128 v[192:195], v210 offset:36864
	ds_read_b128 v[196:199], v210 offset:37888
	ds_read_b128 v[200:203], v210 offset:38912
	ds_read_b128 v[212:215], v210 offset:39936
	global_load_lds_dwordx4 v176, s[36:37]
	s_mov_b32 m0, s43
	s_nop 0
	global_load_lds_dwordx4 v180, s[36:37]
	s_waitcnt vmcnt(8)
	s_waitcnt lgkmcnt(0)
	s_barrier
	s_setprio 1
	s_waitcnt lgkmcnt(0)
	v_mfma_f32_16x16x32_bf16 v[124:127], v[128:131], v[160:163], v[124:127]
	v_mfma_f32_16x16x32_bf16 v[120:123], v[136:139], v[160:163], v[120:123]
	v_mfma_f32_16x16x32_bf16 v[108:111], v[128:131], v[168:171], v[108:111]
	v_mfma_f32_16x16x32_bf16 v[104:107], v[136:139], v[168:171], v[104:107]
	v_mfma_f32_16x16x32_bf16 v[92:95], v[128:131], v[192:195], v[92:95]
	v_mfma_f32_16x16x32_bf16 v[88:91], v[136:139], v[192:195], v[88:91]
	v_mfma_f32_16x16x32_bf16 v[76:79], v[128:131], v[200:203], v[76:79]
	v_mfma_f32_16x16x32_bf16 v[72:75], v[136:139], v[200:203], v[72:75]
	v_mfma_f32_16x16x32_bf16 v[124:127], v[132:135], v[164:167], v[124:127]
	v_mfma_f32_16x16x32_bf16 v[120:123], v[140:143], v[164:167], v[120:123]
	v_mfma_f32_16x16x32_bf16 v[108:111], v[132:135], v[172:175], v[108:111]
	v_mfma_f32_16x16x32_bf16 v[104:107], v[140:143], v[172:175], v[104:107]
	v_mfma_f32_16x16x32_bf16 v[92:95], v[132:135], v[196:199], v[92:95]
	v_mfma_f32_16x16x32_bf16 v[88:91], v[140:143], v[196:199], v[88:91]
	v_mfma_f32_16x16x32_bf16 v[76:79], v[132:135], v[212:215], v[76:79]
	v_mfma_f32_16x16x32_bf16 v[72:75], v[140:143], v[212:215], v[72:75]
	s_setprio 0
	s_setprio 1
	v_mfma_f32_16x16x32_bf16 v[116:119], v[144:147], v[160:163], v[116:119]
	v_mfma_f32_16x16x32_bf16 v[112:115], v[152:155], v[160:163], v[112:115]
	v_mfma_f32_16x16x32_bf16 v[100:103], v[144:147], v[168:171], v[100:103]
	v_mfma_f32_16x16x32_bf16 v[96:99], v[152:155], v[168:171], v[96:99]
	v_mfma_f32_16x16x32_bf16 v[84:87], v[144:147], v[192:195], v[84:87]
	v_mfma_f32_16x16x32_bf16 v[80:83], v[152:155], v[192:195], v[80:83]
	v_mfma_f32_16x16x32_bf16 v[68:71], v[144:147], v[200:203], v[68:71]
	v_mfma_f32_16x16x32_bf16 v[64:67], v[152:155], v[200:203], v[64:67]
	v_mfma_f32_16x16x32_bf16 v[116:119], v[148:151], v[164:167], v[116:119]
	v_mfma_f32_16x16x32_bf16 v[112:115], v[156:159], v[164:167], v[112:115]
	v_mfma_f32_16x16x32_bf16 v[100:103], v[148:151], v[172:175], v[100:103]
	v_mfma_f32_16x16x32_bf16 v[96:99], v[156:159], v[172:175], v[96:99]
	v_mfma_f32_16x16x32_bf16 v[84:87], v[148:151], v[196:199], v[84:87]
	v_mfma_f32_16x16x32_bf16 v[80:83], v[156:159], v[196:199], v[80:83]
	v_mfma_f32_16x16x32_bf16 v[68:71], v[148:151], v[212:215], v[68:71]
	v_mfma_f32_16x16x32_bf16 v[64:67], v[156:159], v[212:215], v[64:67]
	s_setprio 0
	s_barrier
	s_add_i32 s36, s56, s40
	s_mov_b32 m0, s36
	ds_read_b128 v[160:163], v210 offset:49152
	ds_read_b128 v[164:167], v210 offset:50176
	ds_read_b128 v[168:171], v210 offset:51200
	ds_read_b128 v[172:175], v210 offset:52224
	ds_read_b128 v[192:195], v210 offset:53248
	ds_read_b128 v[196:199], v210 offset:54272
	ds_read_b128 v[200:203], v210 offset:55296
	ds_read_b128 v[212:215], v210 offset:56320
	s_add_u32 s98, s34, s14
	s_addc_u32 s99, s35, s15
	global_load_lds_dwordx4 v178, s[98:99]
	s_add_i32 m0, s36, 0x2000
	s_add_u32 s34, s34, 0x40080
	v_lshl_add_u64 v[216:217], v[218:219], 0, s[14:15]
	s_addc_u32 s35, s35, 0
	s_add_i32 s36, s57, s40
	global_load_lds_dwordx4 v[216:217], off
	s_mov_b32 m0, s36
	s_nop 0
	global_load_lds_dwordx4 v178, s[34:35]
	s_add_i32 m0, s36, 0x2000
	s_nop 0
	global_load_lds_dwordx4 v182, s[34:35]
	v_lshl_add_u64 v[216:217], v[220:221], 0, s[14:15]
	s_mov_b32 m0, s45
	s_nop 0
	global_load_lds_dwordx4 v[216:217], off
	v_lshl_add_u64 v[216:217], v[222:223], 0, s[14:15]
	s_mov_b32 m0, s46
	s_nop 0
	global_load_lds_dwordx4 v[216:217], off
	s_waitcnt vmcnt(8)
	s_waitcnt lgkmcnt(0)
	s_barrier
	s_setprio 1
	s_waitcnt lgkmcnt(0)
	v_mfma_f32_16x16x32_bf16 v[60:63], v[128:131], v[160:163], v[60:63]
	v_mfma_f32_16x16x32_bf16 v[56:59], v[136:139], v[160:163], v[56:59]
	v_mfma_f32_16x16x32_bf16 v[44:47], v[128:131], v[168:171], v[44:47]
	v_mfma_f32_16x16x32_bf16 v[40:43], v[136:139], v[168:171], v[40:43]
	v_mfma_f32_16x16x32_bf16 v[28:31], v[128:131], v[192:195], v[28:31]
	v_mfma_f32_16x16x32_bf16 v[24:27], v[136:139], v[192:195], v[24:27]
	v_mfma_f32_16x16x32_bf16 v[12:15], v[128:131], v[200:203], v[12:15]
	v_mfma_f32_16x16x32_bf16 v[8:11], v[136:139], v[200:203], v[8:11]
	v_mfma_f32_16x16x32_bf16 v[60:63], v[132:135], v[164:167], v[60:63]
	v_mfma_f32_16x16x32_bf16 v[56:59], v[140:143], v[164:167], v[56:59]
	v_mfma_f32_16x16x32_bf16 v[44:47], v[132:135], v[172:175], v[44:47]
	v_mfma_f32_16x16x32_bf16 v[40:43], v[140:143], v[172:175], v[40:43]
	v_mfma_f32_16x16x32_bf16 v[28:31], v[132:135], v[196:199], v[28:31]
	v_mfma_f32_16x16x32_bf16 v[24:27], v[140:143], v[196:199], v[24:27]
	v_mfma_f32_16x16x32_bf16 v[12:15], v[132:135], v[212:215], v[12:15]
	v_mfma_f32_16x16x32_bf16 v[8:11], v[140:143], v[212:215], v[8:11]
	s_setprio 0
	s_setprio 1
	v_mfma_f32_16x16x32_bf16 v[52:55], v[144:147], v[160:163], v[52:55]
	v_mfma_f32_16x16x32_bf16 v[48:51], v[152:155], v[160:163], v[48:51]
	v_mfma_f32_16x16x32_bf16 v[36:39], v[144:147], v[168:171], v[36:39]
	v_mfma_f32_16x16x32_bf16 v[32:35], v[152:155], v[168:171], v[32:35]
	v_mfma_f32_16x16x32_bf16 v[20:23], v[144:147], v[192:195], v[20:23]
	v_mfma_f32_16x16x32_bf16 v[16:19], v[152:155], v[192:195], v[16:19]
	v_mfma_f32_16x16x32_bf16 v[4:7], v[144:147], v[200:203], v[4:7]
	v_mfma_f32_16x16x32_bf16 v[0:3], v[152:155], v[200:203], v[0:3]
	v_mfma_f32_16x16x32_bf16 v[52:55], v[148:151], v[164:167], v[52:55]
	v_mfma_f32_16x16x32_bf16 v[48:51], v[156:159], v[164:167], v[48:51]
	v_mfma_f32_16x16x32_bf16 v[36:39], v[148:151], v[172:175], v[36:39]
	v_mfma_f32_16x16x32_bf16 v[32:35], v[156:159], v[172:175], v[32:35]
	v_mfma_f32_16x16x32_bf16 v[20:23], v[148:151], v[196:199], v[20:23]
	v_mfma_f32_16x16x32_bf16 v[16:19], v[156:159], v[196:199], v[16:19]
	v_mfma_f32_16x16x32_bf16 v[4:7], v[148:151], v[212:215], v[4:7]
	v_mfma_f32_16x16x32_bf16 v[0:3], v[156:159], v[212:215], v[0:3]
	s_setprio 0
	s_barrier
	s_add_i32 s55, s55, 2
	s_add_u32 s30, s30, 0x100
	s_addc_u32 s31, s31, 0
	s_add_u32 s53, s53, 0x100
	s_addc_u32 s54, s54, 0
	s_cmp_gt_u32 s55, 13
	s_cbranch_scc0 .LBB0_1046
	s_and_b64 vcc, exec, s[16:17]
	s_cbranch_vccz .LBB0_1049
	s_barrier

.LBB0_1129:
	ds_read_b128 v[144:147], v157
	ds_read_b128 v[148:151], v157 offset:1024
	ds_read_b128 v[162:165], v157 offset:2048
	ds_read_b128 v[166:169], v157 offset:3072
	ds_read_b128 v[170:173], v158
	ds_read_b128 v[174:177], v158 offset:1024
	ds_read_b128 v[178:181], v158 offset:2048
	ds_read_b128 v[182:185], v158 offset:3072
	s_add_u32 s28, s26, 0xfffc0080
	s_addc_u32 s29, s27, -1
	s_cmp_eq_u32 s56, 12
	s_cselect_b32 s31, s21, s29
	s_cselect_b32 s30, s52, s28
	s_cselect_b32 s29, s19, s55
	s_cselect_b32 s28, s53, s54
	s_add_i32 m0, s39, 0xc000
	ds_read_b128 v[186:189], v159
	ds_read_b128 v[190:193], v159 offset:1024
	ds_read_b128 v[194:197], v159 offset:2048
	ds_read_b128 v[198:201], v159 offset:3072
	ds_read_b128 v[202:205], v159 offset:4096
	ds_read_b128 v[210:213], v159 offset:5120
	ds_read_b128 v[214:217], v159 offset:6144
	ds_read_b128 v[218:221], v159 offset:7168
	global_load_lds_dwordx4 v136, s[26:27]
	s_add_i32 m0, s39, 0xe000
	s_nop 0
	global_load_lds_dwordx4 v138, s[26:27]
	s_waitcnt vmcnt(8)
	s_waitcnt lgkmcnt(0)
	s_barrier
	s_setprio 1
	s_waitcnt lgkmcnt(0)
	v_mfma_f32_16x16x32_bf16 v[124:127], v[144:147], v[186:189], v[124:127]
	v_mfma_f32_16x16x32_bf16 v[120:123], v[162:165], v[186:189], v[120:123]
	v_mfma_f32_16x16x32_bf16 v[108:111], v[144:147], v[194:197], v[108:111]
	v_mfma_f32_16x16x32_bf16 v[104:107], v[162:165], v[194:197], v[104:107]
	v_mfma_f32_16x16x32_bf16 v[92:95], v[144:147], v[202:205], v[92:95]
	v_mfma_f32_16x16x32_bf16 v[88:91], v[162:165], v[202:205], v[88:91]
	v_mfma_f32_16x16x32_bf16 v[76:79], v[144:147], v[214:217], v[76:79]
	v_mfma_f32_16x16x32_bf16 v[72:75], v[162:165], v[214:217], v[72:75]
	v_mfma_f32_16x16x32_bf16 v[124:127], v[148:151], v[190:193], v[124:127]
	v_mfma_f32_16x16x32_bf16 v[120:123], v[166:169], v[190:193], v[120:123]
	v_mfma_f32_16x16x32_bf16 v[108:111], v[148:151], v[198:201], v[108:111]
	v_mfma_f32_16x16x32_bf16 v[104:107], v[166:169], v[198:201], v[104:107]
	v_mfma_f32_16x16x32_bf16 v[92:95], v[148:151], v[210:213], v[92:95]
	v_mfma_f32_16x16x32_bf16 v[88:91], v[166:169], v[210:213], v[88:91]
	v_mfma_f32_16x16x32_bf16 v[76:79], v[148:151], v[218:221], v[76:79]
	v_mfma_f32_16x16x32_bf16 v[72:75], v[166:169], v[218:221], v[72:75]
	s_setprio 0
	s_setprio 1
	v_mfma_f32_16x16x32_bf16 v[116:119], v[170:173], v[186:189], v[116:119]
	v_mfma_f32_16x16x32_bf16 v[112:115], v[178:181], v[186:189], v[112:115]
	v_mfma_f32_16x16x32_bf16 v[100:103], v[170:173], v[194:197], v[100:103]
	v_mfma_f32_16x16x32_bf16 v[96:99], v[178:181], v[194:197], v[96:99]
	v_mfma_f32_16x16x32_bf16 v[84:87], v[170:173], v[202:205], v[84:87]
	v_mfma_f32_16x16x32_bf16 v[80:83], v[178:181], v[202:205], v[80:83]
	v_mfma_f32_16x16x32_bf16 v[68:71], v[170:173], v[214:217], v[68:71]
	v_mfma_f32_16x16x32_bf16 v[64:67], v[178:181], v[214:217], v[64:67]
	v_mfma_f32_16x16x32_bf16 v[116:119], v[174:177], v[190:193], v[116:119]
	v_mfma_f32_16x16x32_bf16 v[112:115], v[182:185], v[190:193], v[112:115]
	v_mfma_f32_16x16x32_bf16 v[100:103], v[174:177], v[198:201], v[100:103]
	v_mfma_f32_16x16x32_bf16 v[96:99], v[182:185], v[198:201], v[96:99]
	v_mfma_f32_16x16x32_bf16 v[84:87], v[174:177], v[210:213], v[84:87]
	v_mfma_f32_16x16x32_bf16 v[80:83], v[182:185], v[210:213], v[80:83]
	v_mfma_f32_16x16x32_bf16 v[68:71], v[174:177], v[218:221], v[68:71]
	v_mfma_f32_16x16x32_bf16 v[64:67], v[182:185], v[218:221], v[64:67]
	s_setprio 0
	s_barrier
	s_add_i32 s57, s48, s36
	s_mov_b32 m0, s57
	ds_read_b128 v[186:189], v159 offset:16384
	ds_read_b128 v[190:193], v159 offset:17408
	ds_read_b128 v[194:197], v159 offset:18432
	ds_read_b128 v[198:201], v159 offset:19456
	ds_read_b128 v[202:205], v159 offset:20480
	ds_read_b128 v[210:213], v159 offset:21504
	ds_read_b128 v[214:217], v159 offset:22528
	ds_read_b128 v[218:221], v159 offset:23552
	global_load_lds_dwordx4 v132, s[28:29]
	s_add_i32 m0, s57, 0x2000
	s_add_u32 s58, s28, 0x40000
	v_lshl_add_u64 v[206:207], s[28:29], 0, v[128:129]
	s_addc_u32 s59, s29, 0
	s_add_i32 s57, s49, s36
	global_load_lds_dwordx4 v128, s[28:29]
	s_mov_b32 m0, s57
	v_lshl_add_u64 v[224:225], s[30:31], 0, v[130:131]
	global_load_lds_dwordx4 v132, s[58:59]
	s_add_i32 m0, s57, 0x2000
	s_nop 0
	global_load_lds_dwordx4 v128, s[58:59]
	v_lshl_add_u64 v[222:223], s[30:31], 0, v[134:135]
	s_mov_b32 m0, s39
	s_nop 0
	global_load_lds_dwordx4 v134, s[30:31]
	s_mov_b32 m0, s40
	s_nop 0
	global_load_lds_dwordx4 v130, s[30:31]
	s_waitcnt vmcnt(8)
	s_waitcnt lgkmcnt(0)
	s_barrier
	s_setprio 1
	s_waitcnt lgkmcnt(0)
	v_mfma_f32_16x16x32_bf16 v[60:63], v[144:147], v[186:189], v[60:63]
	v_mfma_f32_16x16x32_bf16 v[56:59], v[162:165], v[186:189], v[56:59]
	v_mfma_f32_16x16x32_bf16 v[44:47], v[144:147], v[194:197], v[44:47]
	v_mfma_f32_16x16x32_bf16 v[40:43], v[162:165], v[194:197], v[40:43]
	v_mfma_f32_16x16x32_bf16 v[28:31], v[144:147], v[202:205], v[28:31]
	v_mfma_f32_16x16x32_bf16 v[24:27], v[162:165], v[202:205], v[24:27]
	v_mfma_f32_16x16x32_bf16 v[12:15], v[144:147], v[214:217], v[12:15]
	v_mfma_f32_16x16x32_bf16 v[8:11], v[162:165], v[214:217], v[8:11]
	v_mfma_f32_16x16x32_bf16 v[60:63], v[148:151], v[190:193], v[60:63]
	v_mfma_f32_16x16x32_bf16 v[56:59], v[166:169], v[190:193], v[56:59]
	v_mfma_f32_16x16x32_bf16 v[44:47], v[148:151], v[198:201], v[44:47]
	v_mfma_f32_16x16x32_bf16 v[40:43], v[166:169], v[198:201], v[40:43]
	v_mfma_f32_16x16x32_bf16 v[28:31], v[148:151], v[210:213], v[28:31]
	v_mfma_f32_16x16x32_bf16 v[24:27], v[166:169], v[210:213], v[24:27]
	v_mfma_f32_16x16x32_bf16 v[12:15], v[148:151], v[218:221], v[12:15]
	v_mfma_f32_16x16x32_bf16 v[8:11], v[166:169], v[218:221], v[8:11]
	s_setprio 0
	s_setprio 1
	v_mfma_f32_16x16x32_bf16 v[52:55], v[170:173], v[186:189], v[52:55]
	v_mfma_f32_16x16x32_bf16 v[48:51], v[178:181], v[186:189], v[48:51]
	v_mfma_f32_16x16x32_bf16 v[36:39], v[170:173], v[194:197], v[36:39]
	v_mfma_f32_16x16x32_bf16 v[32:35], v[178:181], v[194:197], v[32:35]
	v_mfma_f32_16x16x32_bf16 v[20:23], v[170:173], v[202:205], v[20:23]
	v_mfma_f32_16x16x32_bf16 v[16:19], v[178:181], v[202:205], v[16:19]
	v_mfma_f32_16x16x32_bf16 v[4:7], v[170:173], v[214:217], v[4:7]
	v_mfma_f32_16x16x32_bf16 v[0:3], v[178:181], v[214:217], v[0:3]
	v_mfma_f32_16x16x32_bf16 v[52:55], v[174:177], v[190:193], v[52:55]
	v_mfma_f32_16x16x32_bf16 v[48:51], v[182:185], v[190:193], v[48:51]
	v_mfma_f32_16x16x32_bf16 v[36:39], v[174:177], v[198:201], v[36:39]
	v_mfma_f32_16x16x32_bf16 v[32:35], v[182:185], v[198:201], v[32:35]
	v_mfma_f32_16x16x32_bf16 v[20:23], v[174:177], v[210:213], v[20:23]
	v_mfma_f32_16x16x32_bf16 v[16:19], v[182:185], v[210:213], v[16:19]
	v_mfma_f32_16x16x32_bf16 v[4:7], v[174:177], v[218:221], v[4:7]
	v_mfma_f32_16x16x32_bf16 v[0:3], v[182:185], v[218:221], v[0:3]
	s_setprio 0
	s_barrier
	s_add_i32 s57, 0, 0x18000
	v_add_u32_e32 v161, s57, v155
	s_add_i32 s58, 0, 0x1c000
	ds_read_b128 v[144:147], v161
	ds_read_b128 v[148:151], v161 offset:1024
	ds_read_b128 v[162:165], v161 offset:2048
	ds_read_b128 v[166:169], v161 offset:3072
	v_add_u32_e32 v161, s58, v155
	ds_read_b128 v[170:173], v161
	ds_read_b128 v[174:177], v161 offset:1024
	ds_read_b128 v[178:181], v161 offset:2048
	ds_read_b128 v[182:185], v161 offset:3072
	s_add_u32 s30, s30, 0x40000
	s_addc_u32 s31, s31, 0
	s_mov_b32 m0, s41
	ds_read_b128 v[186:189], v159 offset:32768
	ds_read_b128 v[190:193], v159 offset:33792
	ds_read_b128 v[194:197], v159 offset:34816
	ds_read_b128 v[198:201], v159 offset:35840
	ds_read_b128 v[202:205], v159 offset:36864
	ds_read_b128 v[210:213], v159 offset:37888
	ds_read_b128 v[214:217], v159 offset:38912
	ds_read_b128 v[218:221], v159 offset:39936
	global_load_lds_dwordx4 v134, s[30:31]
	s_mov_b32 m0, s42
	s_nop 0
	global_load_lds_dwordx4 v130, s[30:31]
	s_waitcnt vmcnt(8)
	s_waitcnt lgkmcnt(0)
	s_barrier
	s_setprio 1
	s_waitcnt lgkmcnt(0)
	v_mfma_f32_16x16x32_bf16 v[124:127], v[144:147], v[186:189], v[124:127]
	v_mfma_f32_16x16x32_bf16 v[120:123], v[162:165], v[186:189], v[120:123]
	v_mfma_f32_16x16x32_bf16 v[108:111], v[144:147], v[194:197], v[108:111]
	v_mfma_f32_16x16x32_bf16 v[104:107], v[162:165], v[194:197], v[104:107]
	v_mfma_f32_16x16x32_bf16 v[92:95], v[144:147], v[202:205], v[92:95]
	v_mfma_f32_16x16x32_bf16 v[88:91], v[162:165], v[202:205], v[88:91]
	v_mfma_f32_16x16x32_bf16 v[76:79], v[144:147], v[214:217], v[76:79]
	v_mfma_f32_16x16x32_bf16 v[72:75], v[162:165], v[214:217], v[72:75]
	v_mfma_f32_16x16x32_bf16 v[124:127], v[148:151], v[190:193], v[124:127]
	v_mfma_f32_16x16x32_bf16 v[120:123], v[166:169], v[190:193], v[120:123]
	v_mfma_f32_16x16x32_bf16 v[108:111], v[148:151], v[198:201], v[108:111]
	v_mfma_f32_16x16x32_bf16 v[104:107], v[166:169], v[198:201], v[104:107]
	v_mfma_f32_16x16x32_bf16 v[92:95], v[148:151], v[210:213], v[92:95]
	v_mfma_f32_16x16x32_bf16 v[88:91], v[166:169], v[210:213], v[88:91]
	v_mfma_f32_16x16x32_bf16 v[76:79], v[148:151], v[218:221], v[76:79]
	v_mfma_f32_16x16x32_bf16 v[72:75], v[166:169], v[218:221], v[72:75]
	s_setprio 0
	s_setprio 1
	v_mfma_f32_16x16x32_bf16 v[116:119], v[170:173], v[186:189], v[116:119]
	v_mfma_f32_16x16x32_bf16 v[112:115], v[178:181], v[186:189], v[112:115]
	v_mfma_f32_16x16x32_bf16 v[100:103], v[170:173], v[194:197], v[100:103]
	v_mfma_f32_16x16x32_bf16 v[96:99], v[178:181], v[194:197], v[96:99]
	v_mfma_f32_16x16x32_bf16 v[84:87], v[170:173], v[202:205], v[84:87]
	v_mfma_f32_16x16x32_bf16 v[80:83], v[178:181], v[202:205], v[80:83]
	v_mfma_f32_16x16x32_bf16 v[68:71], v[170:173], v[214:217], v[68:71]
	v_mfma_f32_16x16x32_bf16 v[64:67], v[178:181], v[214:217], v[64:67]
	v_mfma_f32_16x16x32_bf16 v[116:119], v[174:177], v[190:193], v[116:119]
	v_mfma_f32_16x16x32_bf16 v[112:115], v[182:185], v[190:193], v[112:115]
	v_mfma_f32_16x16x32_bf16 v[100:103], v[174:177], v[198:201], v[100:103]
	v_mfma_f32_16x16x32_bf16 v[96:99], v[182:185], v[198:201], v[96:99]
	v_mfma_f32_16x16x32_bf16 v[84:87], v[174:177], v[210:213], v[84:87]
	v_mfma_f32_16x16x32_bf16 v[80:83], v[182:185], v[210:213], v[80:83]
	v_mfma_f32_16x16x32_bf16 v[68:71], v[174:177], v[218:221], v[68:71]
	v_mfma_f32_16x16x32_bf16 v[64:67], v[182:185], v[218:221], v[64:67]
	s_setprio 0
	s_barrier
	s_add_i32 s30, s57, s36
	s_mov_b32 m0, s30
	ds_read_b128 v[186:189], v159 offset:49152
	ds_read_b128 v[190:193], v159 offset:50176
	ds_read_b128 v[194:197], v159 offset:51200
	ds_read_b128 v[198:201], v159 offset:52224
	ds_read_b128 v[202:205], v159 offset:53248
	ds_read_b128 v[210:213], v159 offset:54272
	ds_read_b128 v[214:217], v159 offset:55296
	ds_read_b128 v[218:221], v159 offset:56320
	s_add_u32 s98, s28, s14
	s_addc_u32 s99, s29, s15
	global_load_lds_dwordx4 v132, s[98:99]
	s_add_i32 m0, s30, 0x2000
	s_add_u32 s28, s28, 0x40080
	v_lshl_add_u64 v[152:153], v[206:207], 0, s[14:15]
	s_addc_u32 s29, s29, 0
	s_add_i32 s30, s58, s36
	global_load_lds_dwordx4 v[152:153], off
	s_mov_b32 m0, s30
	s_nop 0
	global_load_lds_dwordx4 v132, s[28:29]
	s_add_i32 m0, s30, 0x2000
	s_nop 0
	global_load_lds_dwordx4 v128, s[28:29]
	v_lshl_add_u64 v[152:153], v[222:223], 0, s[14:15]
	s_mov_b32 m0, s44
	s_nop 0
	global_load_lds_dwordx4 v[152:153], off
	v_lshl_add_u64 v[152:153], v[224:225], 0, s[14:15]
	s_mov_b32 m0, s45
	s_nop 0
	global_load_lds_dwordx4 v[152:153], off
	s_waitcnt vmcnt(8)
	s_waitcnt lgkmcnt(0)
	s_barrier
	s_setprio 1
	s_waitcnt lgkmcnt(0)
	v_mfma_f32_16x16x32_bf16 v[60:63], v[144:147], v[186:189], v[60:63]
	v_mfma_f32_16x16x32_bf16 v[56:59], v[162:165], v[186:189], v[56:59]
	v_mfma_f32_16x16x32_bf16 v[44:47], v[144:147], v[194:197], v[44:47]
	v_mfma_f32_16x16x32_bf16 v[40:43], v[162:165], v[194:197], v[40:43]
	v_mfma_f32_16x16x32_bf16 v[28:31], v[144:147], v[202:205], v[28:31]
	v_mfma_f32_16x16x32_bf16 v[24:27], v[162:165], v[202:205], v[24:27]
	v_mfma_f32_16x16x32_bf16 v[12:15], v[144:147], v[214:217], v[12:15]
	v_mfma_f32_16x16x32_bf16 v[8:11], v[162:165], v[214:217], v[8:11]
	v_mfma_f32_16x16x32_bf16 v[60:63], v[148:151], v[190:193], v[60:63]
	v_mfma_f32_16x16x32_bf16 v[56:59], v[166:169], v[190:193], v[56:59]
	v_mfma_f32_16x16x32_bf16 v[44:47], v[148:151], v[198:201], v[44:47]
	v_mfma_f32_16x16x32_bf16 v[40:43], v[166:169], v[198:201], v[40:43]
	v_mfma_f32_16x16x32_bf16 v[28:31], v[148:151], v[210:213], v[28:31]
	v_mfma_f32_16x16x32_bf16 v[24:27], v[166:169], v[210:213], v[24:27]
	v_mfma_f32_16x16x32_bf16 v[12:15], v[148:151], v[218:221], v[12:15]
	v_mfma_f32_16x16x32_bf16 v[8:11], v[166:169], v[218:221], v[8:11]
	s_setprio 0
	s_setprio 1
	v_mfma_f32_16x16x32_bf16 v[52:55], v[170:173], v[186:189], v[52:55]
	v_mfma_f32_16x16x32_bf16 v[48:51], v[178:181], v[186:189], v[48:51]
	v_mfma_f32_16x16x32_bf16 v[36:39], v[170:173], v[194:197], v[36:39]
	v_mfma_f32_16x16x32_bf16 v[32:35], v[178:181], v[194:197], v[32:35]
	v_mfma_f32_16x16x32_bf16 v[20:23], v[170:173], v[202:205], v[20:23]
	v_mfma_f32_16x16x32_bf16 v[16:19], v[178:181], v[202:205], v[16:19]
	v_mfma_f32_16x16x32_bf16 v[4:7], v[170:173], v[214:217], v[4:7]
	v_mfma_f32_16x16x32_bf16 v[0:3], v[178:181], v[214:217], v[0:3]
	v_mfma_f32_16x16x32_bf16 v[52:55], v[174:177], v[190:193], v[52:55]
	v_mfma_f32_16x16x32_bf16 v[48:51], v[182:185], v[190:193], v[48:51]
	v_mfma_f32_16x16x32_bf16 v[36:39], v[174:177], v[198:201], v[36:39]
	v_mfma_f32_16x16x32_bf16 v[32:35], v[182:185], v[198:201], v[32:35]
	v_mfma_f32_16x16x32_bf16 v[20:23], v[174:177], v[210:213], v[20:23]
	v_mfma_f32_16x16x32_bf16 v[16:19], v[182:185], v[210:213], v[16:19]
	v_mfma_f32_16x16x32_bf16 v[4:7], v[174:177], v[218:221], v[4:7]
	v_mfma_f32_16x16x32_bf16 v[0:3], v[182:185], v[218:221], v[0:3]
	s_setprio 0
	s_barrier
	s_add_i32 s56, s56, 2
	s_add_u32 s26, s26, 0x100
	s_addc_u32 s27, s27, 0
	s_add_u32 s54, s54, 0x100
	s_addc_u32 s55, s55, 0
	s_cmp_gt_u32 s56, 13
	s_cbranch_scc0 .LBB0_1129
	s_and_b64 vcc, exec, s[16:17]
	s_cbranch_vccz .LBB0_1132
	s_barrier

.LBB0_1210:
	ds_read_b128 v[128:131], v189
	ds_read_b128 v[132:135], v189 offset:1024
	ds_read_b128 v[136:139], v189 offset:2048
	ds_read_b128 v[140:143], v189 offset:3072
	ds_read_b128 v[144:147], v190
	ds_read_b128 v[148:151], v190 offset:1024
	ds_read_b128 v[168:171], v190 offset:2048
	ds_read_b128 v[172:175], v190 offset:3072
	s_add_u32 s26, s24, 0x100
	s_addc_u32 s27, s25, 0
	s_cmp_eq_u32 s55, 40
	s_cselect_b32 s31, s5, s27
	s_cselect_b32 s30, s4, s26
	s_cselect_b32 s29, s23, s54
	s_cselect_b32 s28, s22, s53
	s_add_i32 m0, s37, 0xc000
	ds_read_b128 v[176:179], v191
	ds_read_b128 v[180:183], v191 offset:1024
	ds_read_b128 v[194:197], v191 offset:2048
	ds_read_b128 v[198:201], v191 offset:3072
	ds_read_b128 v[202:205], v191 offset:4096
	ds_read_b128 v[210:213], v191 offset:5120
	ds_read_b128 v[214:217], v191 offset:6144
	ds_read_b128 v[218:221], v191 offset:7168
	global_load_lds_dwordx4 v160, s[24:25]
	s_add_i32 m0, s37, 0xe000
	s_nop 0
	global_load_lds_dwordx4 v162, s[24:25]
	s_waitcnt vmcnt(8)
	s_waitcnt lgkmcnt(0)
	s_barrier
	s_setprio 1
	s_waitcnt lgkmcnt(0)
	v_mfma_f32_16x16x32_bf16 v[124:127], v[128:131], v[176:179], v[124:127]
	v_mfma_f32_16x16x32_bf16 v[120:123], v[136:139], v[176:179], v[120:123]
	v_mfma_f32_16x16x32_bf16 v[108:111], v[128:131], v[194:197], v[108:111]
	v_mfma_f32_16x16x32_bf16 v[104:107], v[136:139], v[194:197], v[104:107]
	v_mfma_f32_16x16x32_bf16 v[92:95], v[128:131], v[202:205], v[92:95]
	v_mfma_f32_16x16x32_bf16 v[88:91], v[136:139], v[202:205], v[88:91]
	v_mfma_f32_16x16x32_bf16 v[76:79], v[128:131], v[214:217], v[76:79]
	v_mfma_f32_16x16x32_bf16 v[72:75], v[136:139], v[214:217], v[72:75]
	v_mfma_f32_16x16x32_bf16 v[124:127], v[132:135], v[180:183], v[124:127]
	v_mfma_f32_16x16x32_bf16 v[120:123], v[140:143], v[180:183], v[120:123]
	v_mfma_f32_16x16x32_bf16 v[108:111], v[132:135], v[198:201], v[108:111]
	v_mfma_f32_16x16x32_bf16 v[104:107], v[140:143], v[198:201], v[104:107]
	v_mfma_f32_16x16x32_bf16 v[92:95], v[132:135], v[210:213], v[92:95]
	v_mfma_f32_16x16x32_bf16 v[88:91], v[140:143], v[210:213], v[88:91]
	v_mfma_f32_16x16x32_bf16 v[76:79], v[132:135], v[218:221], v[76:79]
	v_mfma_f32_16x16x32_bf16 v[72:75], v[140:143], v[218:221], v[72:75]
	s_setprio 0
	s_setprio 1
	v_mfma_f32_16x16x32_bf16 v[116:119], v[144:147], v[176:179], v[116:119]
	v_mfma_f32_16x16x32_bf16 v[112:115], v[168:171], v[176:179], v[112:115]
	v_mfma_f32_16x16x32_bf16 v[100:103], v[144:147], v[194:197], v[100:103]
	v_mfma_f32_16x16x32_bf16 v[96:99], v[168:171], v[194:197], v[96:99]
	v_mfma_f32_16x16x32_bf16 v[84:87], v[144:147], v[202:205], v[84:87]
	v_mfma_f32_16x16x32_bf16 v[80:83], v[168:171], v[202:205], v[80:83]
	v_mfma_f32_16x16x32_bf16 v[68:71], v[144:147], v[214:217], v[68:71]
	v_mfma_f32_16x16x32_bf16 v[64:67], v[168:171], v[214:217], v[64:67]
	v_mfma_f32_16x16x32_bf16 v[116:119], v[148:151], v[180:183], v[116:119]
	v_mfma_f32_16x16x32_bf16 v[112:115], v[172:175], v[180:183], v[112:115]
	v_mfma_f32_16x16x32_bf16 v[100:103], v[148:151], v[198:201], v[100:103]
	v_mfma_f32_16x16x32_bf16 v[96:99], v[172:175], v[198:201], v[96:99]
	v_mfma_f32_16x16x32_bf16 v[84:87], v[148:151], v[210:213], v[84:87]
	v_mfma_f32_16x16x32_bf16 v[80:83], v[172:175], v[210:213], v[80:83]
	v_mfma_f32_16x16x32_bf16 v[68:71], v[148:151], v[218:221], v[68:71]
	v_mfma_f32_16x16x32_bf16 v[64:67], v[172:175], v[218:221], v[64:67]
	s_setprio 0
	s_barrier
	s_add_i32 s24, s47, s36
	s_mov_b32 m0, s24
	ds_read_b128 v[176:179], v191 offset:16384
	ds_read_b128 v[180:183], v191 offset:17408
	ds_read_b128 v[194:197], v191 offset:18432
	ds_read_b128 v[198:201], v191 offset:19456
	ds_read_b128 v[202:205], v191 offset:20480
	ds_read_b128 v[210:213], v191 offset:21504
	ds_read_b128 v[214:217], v191 offset:22528
	ds_read_b128 v[218:221], v191 offset:23552
	global_load_lds_dwordx4 v154, s[28:29]
	s_add_i32 m0, s24, 0x2000
	s_add_u32 s24, s28, 0xb0000
	v_lshl_add_u64 v[206:207], s[28:29], 0, v[158:159]
	s_addc_u32 s25, s29, 0
	s_add_i32 s56, s48, s36
	global_load_lds_dwordx4 v158, s[28:29]
	s_mov_b32 m0, s56
	global_load_lds_dwordx4 v154, s[24:25]
	s_add_i32 m0, s56, 0x2000
	s_nop 0
	global_load_lds_dwordx4 v158, s[24:25]
	s_mov_b32 m0, s37
	s_nop 0
	global_load_lds_dwordx4 v152, s[30:31]
	s_mov_b32 m0, s38
	s_nop 0
	global_load_lds_dwordx4 v156, s[30:31]
	s_waitcnt vmcnt(8)
	s_waitcnt lgkmcnt(0)
	s_barrier
	s_setprio 1
	s_waitcnt lgkmcnt(0)
	v_mfma_f32_16x16x32_bf16 v[60:63], v[128:131], v[176:179], v[60:63]
	v_mfma_f32_16x16x32_bf16 v[56:59], v[136:139], v[176:179], v[56:59]
	v_mfma_f32_16x16x32_bf16 v[44:47], v[128:131], v[194:197], v[44:47]
	v_mfma_f32_16x16x32_bf16 v[40:43], v[136:139], v[194:197], v[40:43]
	v_mfma_f32_16x16x32_bf16 v[28:31], v[128:131], v[202:205], v[28:31]
	v_mfma_f32_16x16x32_bf16 v[24:27], v[136:139], v[202:205], v[24:27]
	v_mfma_f32_16x16x32_bf16 v[12:15], v[128:131], v[214:217], v[12:15]
	v_mfma_f32_16x16x32_bf16 v[8:11], v[136:139], v[214:217], v[8:11]
	v_mfma_f32_16x16x32_bf16 v[60:63], v[132:135], v[180:183], v[60:63]
	v_mfma_f32_16x16x32_bf16 v[56:59], v[140:143], v[180:183], v[56:59]
	v_mfma_f32_16x16x32_bf16 v[44:47], v[132:135], v[198:201], v[44:47]
	v_mfma_f32_16x16x32_bf16 v[40:43], v[140:143], v[198:201], v[40:43]
	v_mfma_f32_16x16x32_bf16 v[28:31], v[132:135], v[210:213], v[28:31]
	v_mfma_f32_16x16x32_bf16 v[24:27], v[140:143], v[210:213], v[24:27]
	v_mfma_f32_16x16x32_bf16 v[12:15], v[132:135], v[218:221], v[12:15]
	v_mfma_f32_16x16x32_bf16 v[8:11], v[140:143], v[218:221], v[8:11]
	s_setprio 0
	s_setprio 1
	v_mfma_f32_16x16x32_bf16 v[52:55], v[144:147], v[176:179], v[52:55]
	v_mfma_f32_16x16x32_bf16 v[48:51], v[168:171], v[176:179], v[48:51]
	v_mfma_f32_16x16x32_bf16 v[36:39], v[144:147], v[194:197], v[36:39]
	v_mfma_f32_16x16x32_bf16 v[32:35], v[168:171], v[194:197], v[32:35]
	v_mfma_f32_16x16x32_bf16 v[20:23], v[144:147], v[202:205], v[20:23]
	v_mfma_f32_16x16x32_bf16 v[16:19], v[168:171], v[202:205], v[16:19]
	v_mfma_f32_16x16x32_bf16 v[4:7], v[144:147], v[214:217], v[4:7]
	v_mfma_f32_16x16x32_bf16 v[0:3], v[168:171], v[214:217], v[0:3]
	v_mfma_f32_16x16x32_bf16 v[52:55], v[148:151], v[180:183], v[52:55]
	v_mfma_f32_16x16x32_bf16 v[48:51], v[172:175], v[180:183], v[48:51]
	v_mfma_f32_16x16x32_bf16 v[36:39], v[148:151], v[198:201], v[36:39]
	v_mfma_f32_16x16x32_bf16 v[32:35], v[172:175], v[198:201], v[32:35]
	v_mfma_f32_16x16x32_bf16 v[20:23], v[148:151], v[210:213], v[20:23]
	v_mfma_f32_16x16x32_bf16 v[16:19], v[172:175], v[210:213], v[16:19]
	v_mfma_f32_16x16x32_bf16 v[4:7], v[148:151], v[218:221], v[4:7]
	v_mfma_f32_16x16x32_bf16 v[0:3], v[172:175], v[218:221], v[0:3]
	s_setprio 0
	s_barrier
	s_add_i32 s56, 0, 0x18000
	s_add_i32 s57, 0, 0x1c000
	v_add_u32_e32 v140, s56, v187
	v_add_u32_e32 v172, s57, v187
	ds_read_b128 v[128:131], v140
	ds_read_b128 v[132:135], v140 offset:1024
	ds_read_b128 v[136:139], v140 offset:2048
	ds_read_b128 v[140:143], v140 offset:3072
	ds_read_b128 v[144:147], v172
	ds_read_b128 v[148:151], v172 offset:1024
	ds_read_b128 v[168:171], v172 offset:2048
	ds_read_b128 v[172:175], v172 offset:3072
	s_add_u32 s24, s30, 0xb0000
	s_addc_u32 s25, s31, 0
	s_mov_b32 m0, s39
	ds_read_b128 v[176:179], v191 offset:32768
	ds_read_b128 v[180:183], v191 offset:33792
	ds_read_b128 v[194:197], v191 offset:34816
	ds_read_b128 v[198:201], v191 offset:35840
	ds_read_b128 v[202:205], v191 offset:36864
	ds_read_b128 v[210:213], v191 offset:37888
	ds_read_b128 v[214:217], v191 offset:38912
	ds_read_b128 v[218:221], v191 offset:39936
	global_load_lds_dwordx4 v152, s[24:25]
	s_mov_b32 m0, s40
	s_nop 0
	global_load_lds_dwordx4 v156, s[24:25]
	s_waitcnt vmcnt(8)
	s_waitcnt lgkmcnt(0)
	s_barrier
	s_setprio 1
	s_waitcnt lgkmcnt(0)
	v_mfma_f32_16x16x32_bf16 v[124:127], v[128:131], v[176:179], v[124:127]
	v_mfma_f32_16x16x32_bf16 v[120:123], v[136:139], v[176:179], v[120:123]
	v_mfma_f32_16x16x32_bf16 v[108:111], v[128:131], v[194:197], v[108:111]
	v_mfma_f32_16x16x32_bf16 v[104:107], v[136:139], v[194:197], v[104:107]
	v_mfma_f32_16x16x32_bf16 v[92:95], v[128:131], v[202:205], v[92:95]
	v_mfma_f32_16x16x32_bf16 v[88:91], v[136:139], v[202:205], v[88:91]
	v_mfma_f32_16x16x32_bf16 v[76:79], v[128:131], v[214:217], v[76:79]
	v_mfma_f32_16x16x32_bf16 v[72:75], v[136:139], v[214:217], v[72:75]
	v_mfma_f32_16x16x32_bf16 v[124:127], v[132:135], v[180:183], v[124:127]
	v_mfma_f32_16x16x32_bf16 v[120:123], v[140:143], v[180:183], v[120:123]
	v_mfma_f32_16x16x32_bf16 v[108:111], v[132:135], v[198:201], v[108:111]
	v_mfma_f32_16x16x32_bf16 v[104:107], v[140:143], v[198:201], v[104:107]
	v_mfma_f32_16x16x32_bf16 v[92:95], v[132:135], v[210:213], v[92:95]
	v_mfma_f32_16x16x32_bf16 v[88:91], v[140:143], v[210:213], v[88:91]
	v_mfma_f32_16x16x32_bf16 v[76:79], v[132:135], v[218:221], v[76:79]
	v_mfma_f32_16x16x32_bf16 v[72:75], v[140:143], v[218:221], v[72:75]
	s_setprio 0
	s_setprio 1
	v_mfma_f32_16x16x32_bf16 v[116:119], v[144:147], v[176:179], v[116:119]
	v_mfma_f32_16x16x32_bf16 v[112:115], v[168:171], v[176:179], v[112:115]
	v_mfma_f32_16x16x32_bf16 v[100:103], v[144:147], v[194:197], v[100:103]
	v_mfma_f32_16x16x32_bf16 v[96:99], v[168:171], v[194:197], v[96:99]
	v_mfma_f32_16x16x32_bf16 v[84:87], v[144:147], v[202:205], v[84:87]
	v_mfma_f32_16x16x32_bf16 v[80:83], v[168:171], v[202:205], v[80:83]
	v_mfma_f32_16x16x32_bf16 v[68:71], v[144:147], v[214:217], v[68:71]
	v_mfma_f32_16x16x32_bf16 v[64:67], v[168:171], v[214:217], v[64:67]
	v_mfma_f32_16x16x32_bf16 v[116:119], v[148:151], v[180:183], v[116:119]
	v_mfma_f32_16x16x32_bf16 v[112:115], v[172:175], v[180:183], v[112:115]
	v_mfma_f32_16x16x32_bf16 v[100:103], v[148:151], v[198:201], v[100:103]
	v_mfma_f32_16x16x32_bf16 v[96:99], v[172:175], v[198:201], v[96:99]
	v_mfma_f32_16x16x32_bf16 v[84:87], v[148:151], v[210:213], v[84:87]
	v_mfma_f32_16x16x32_bf16 v[80:83], v[172:175], v[210:213], v[80:83]
	v_mfma_f32_16x16x32_bf16 v[68:71], v[148:151], v[218:221], v[68:71]
	v_mfma_f32_16x16x32_bf16 v[64:67], v[172:175], v[218:221], v[64:67]
	s_setprio 0
	s_barrier
	s_add_i32 s24, s56, s36
	s_mov_b32 m0, s24
	ds_read_b128 v[176:179], v191 offset:49152
	ds_read_b128 v[180:183], v191 offset:50176
	ds_read_b128 v[194:197], v191 offset:51200
	ds_read_b128 v[198:201], v191 offset:52224
	ds_read_b128 v[202:205], v191 offset:53248
	ds_read_b128 v[210:213], v191 offset:54272
	ds_read_b128 v[214:217], v191 offset:55296
	ds_read_b128 v[218:221], v191 offset:56320
	s_add_u32 s98, s28, s18
	s_addc_u32 s99, s29, s19
	global_load_lds_dwordx4 v154, s[98:99]
	s_add_i32 m0, s24, 0x2000
	s_add_u32 s24, s28, 0xb0080
	v_lshl_add_u64 v[184:185], v[206:207], 0, s[18:19]
	s_addc_u32 s25, s29, 0
	s_add_i32 s28, s57, s36
	global_load_lds_dwordx4 v[184:185], off
	s_mov_b32 m0, s28
	s_nop 0
	global_load_lds_dwordx4 v154, s[24:25]
	s_add_i32 m0, s28, 0x2000
	s_nop 0
	global_load_lds_dwordx4 v158, s[24:25]
	s_mov_b32 m0, s42
	s_nop 0
	s_add_u32 s100, s30, s18
	s_addc_u32 s101, s31, s19
	global_load_lds_dwordx4 v152, s[100:101]
	s_mov_b32 m0, s43
	s_nop 0
	s_add_u32 s98, s30, s18
	s_addc_u32 s99, s31, s19
	global_load_lds_dwordx4 v156, s[98:99]
	s_waitcnt vmcnt(8)
	s_waitcnt lgkmcnt(0)
	s_barrier
	s_setprio 1
	s_waitcnt lgkmcnt(0)
	v_mfma_f32_16x16x32_bf16 v[60:63], v[128:131], v[176:179], v[60:63]
	v_mfma_f32_16x16x32_bf16 v[56:59], v[136:139], v[176:179], v[56:59]
	v_mfma_f32_16x16x32_bf16 v[44:47], v[128:131], v[194:197], v[44:47]
	v_mfma_f32_16x16x32_bf16 v[40:43], v[136:139], v[194:197], v[40:43]
	v_mfma_f32_16x16x32_bf16 v[28:31], v[128:131], v[202:205], v[28:31]
	v_mfma_f32_16x16x32_bf16 v[24:27], v[136:139], v[202:205], v[24:27]
	v_mfma_f32_16x16x32_bf16 v[12:15], v[128:131], v[214:217], v[12:15]
	v_mfma_f32_16x16x32_bf16 v[8:11], v[136:139], v[214:217], v[8:11]
	v_mfma_f32_16x16x32_bf16 v[60:63], v[132:135], v[180:183], v[60:63]
	v_mfma_f32_16x16x32_bf16 v[56:59], v[140:143], v[180:183], v[56:59]
	v_mfma_f32_16x16x32_bf16 v[44:47], v[132:135], v[198:201], v[44:47]
	v_mfma_f32_16x16x32_bf16 v[40:43], v[140:143], v[198:201], v[40:43]
	v_mfma_f32_16x16x32_bf16 v[28:31], v[132:135], v[210:213], v[28:31]
	v_mfma_f32_16x16x32_bf16 v[24:27], v[140:143], v[210:213], v[24:27]
	v_mfma_f32_16x16x32_bf16 v[12:15], v[132:135], v[218:221], v[12:15]
	v_mfma_f32_16x16x32_bf16 v[8:11], v[140:143], v[218:221], v[8:11]
	s_setprio 0
	s_setprio 1
	v_mfma_f32_16x16x32_bf16 v[52:55], v[144:147], v[176:179], v[52:55]
	v_mfma_f32_16x16x32_bf16 v[48:51], v[168:171], v[176:179], v[48:51]
	v_mfma_f32_16x16x32_bf16 v[36:39], v[144:147], v[194:197], v[36:39]
	v_mfma_f32_16x16x32_bf16 v[32:35], v[168:171], v[194:197], v[32:35]
	v_mfma_f32_16x16x32_bf16 v[20:23], v[144:147], v[202:205], v[20:23]
	v_mfma_f32_16x16x32_bf16 v[16:19], v[168:171], v[202:205], v[16:19]
	v_mfma_f32_16x16x32_bf16 v[4:7], v[144:147], v[214:217], v[4:7]
	v_mfma_f32_16x16x32_bf16 v[0:3], v[168:171], v[214:217], v[0:3]
	v_mfma_f32_16x16x32_bf16 v[52:55], v[148:151], v[180:183], v[52:55]
	v_mfma_f32_16x16x32_bf16 v[48:51], v[172:175], v[180:183], v[48:51]
	v_mfma_f32_16x16x32_bf16 v[36:39], v[148:151], v[198:201], v[36:39]
	v_mfma_f32_16x16x32_bf16 v[32:35], v[172:175], v[198:201], v[32:35]
	v_mfma_f32_16x16x32_bf16 v[20:23], v[148:151], v[210:213], v[20:23]
	v_mfma_f32_16x16x32_bf16 v[16:19], v[172:175], v[210:213], v[16:19]
	v_mfma_f32_16x16x32_bf16 v[4:7], v[148:151], v[218:221], v[4:7]
	v_mfma_f32_16x16x32_bf16 v[0:3], v[172:175], v[218:221], v[0:3]
	s_setprio 0
	s_barrier
	s_add_i32 s55, s55, 2
	s_add_u32 s53, s53, 0x100
	s_addc_u32 s54, s54, 0
	s_cmp_gt_u32 s55, 41
	s_mov_b64 s[24:25], s[26:27]
	s_cbranch_scc0 .LBB0_1210
	s_and_b64 vcc, exec, s[20:21]
	s_cbranch_vccz .LBB0_1213
	s_barrier
